# selected loop: eight exps (instead of four) issued ahead of the first K-fragment wait at the step head
# baseline (speedup 1.0000x reference)
.Lsel_nodiag_0b:
	v_add_u32_e32 v187, s81, v208
	ds_read_b128 v[124:127], v187 offset:9216
	ds_read_b128 v[144:147], v187 offset:13824
	ds_read_b128 v[148:151], v187 offset:9248
	v_exp_f32_e32 v80, v80
	v_exp_f32_e32 v81, v81
	v_exp_f32_e32 v82, v82
	v_exp_f32_e32 v83, v83
	v_exp_f32_e32 v84, v84
	v_exp_f32_e32 v85, v85
	v_exp_f32_e32 v86, v86
	v_exp_f32_e32 v87, v87
	s_waitcnt lgkmcnt(6)
	v_mfma_f32_32x32x16_bf16 v[238:253], v[108:111], v[128:131], v[2:17]
	ds_read_b128 v[108:111], v0 offset:64
	s_waitcnt lgkmcnt(6)
	v_mfma_f32_32x32x16_bf16 v[222:237], v[112:115], v[128:131], v[2:17]
	ds_read_b128 v[112:115], v0 offset:4672
	v_add_f32_e32 v164, 0, v80
	v_add_f32_e32 v165, 0, v81
	v_add_f32_e32 v164, v82, v164
	v_add_f32_e32 v165, v83, v165
	v_cvt_pk_bf16_f32 v80, v80, v81
	v_cvt_pk_bf16_f32 v81, v82, v83
	v_add_f32_e32 v164, v84, v164
	v_add_f32_e32 v165, v85, v165
	v_add_f32_e32 v164, v86, v164
	v_add_f32_e32 v165, v87, v165
	v_cvt_pk_bf16_f32 v82, v84, v85
	v_cvt_pk_bf16_f32 v83, v86, v87
	v_cndmask_b32_e64 v80, v80, 0, s[72:73]
	v_cndmask_b32_e64 v81, v81, 0, s[72:73]
	v_cndmask_b32_e64 v82, v82, 0, s[72:73]
	v_cndmask_b32_e64 v83, v83, 0, s[72:73]
	v_exp_f32_e32 v88, v88
	v_exp_f32_e32 v89, v89
	s_waitcnt lgkmcnt(4)
	v_mfma_f32_32x32x16_bf16 v[48:63], v[124:127], v[80:83], v[48:63]
	ds_read_b128 v[124:127], v187 offset:13856
	v_exp_f32_e32 v90, v90
	v_exp_f32_e32 v91, v91
	s_waitcnt lgkmcnt(4)
	v_mfma_f32_32x32x16_bf16 v[32:47], v[144:147], v[80:83], v[32:47]
	ds_read_b128 v[144:147], v187 offset:9280
	v_exp_f32_e32 v92, v92
	v_exp_f32_e32 v93, v93
	v_mfma_f32_32x32x16_bf16 v[238:253], v[116:119], v[132:135], v[238:253]
	ds_read_b128 v[116:119], v0 offset:96
	v_exp_f32_e32 v94, v94
	v_exp_f32_e32 v95, v95
	v_mfma_f32_32x32x16_bf16 v[222:237], v[120:123], v[132:135], v[222:237]
	ds_read_b128 v[120:123], v0 offset:4704
	v_add_f32_e32 v164, v88, v164
	v_add_f32_e32 v165, v89, v165
	v_add_f32_e32 v164, v90, v164
	v_add_f32_e32 v165, v91, v165
	v_cvt_pk_bf16_f32 v88, v88, v89
	v_cvt_pk_bf16_f32 v89, v90, v91
	v_add_f32_e32 v164, v92, v164
	v_add_f32_e32 v165, v93, v165
	v_add_f32_e32 v164, v94, v164
	v_add_f32_e32 v165, v95, v165
	v_cvt_pk_bf16_f32 v90, v92, v93
	v_cvt_pk_bf16_f32 v91, v94, v95
	v_cndmask_b32_e64 v88, v88, 0, s[72:73]
	v_cndmask_b32_e64 v89, v89, 0, s[72:73]
	v_cndmask_b32_e64 v90, v90, 0, s[72:73]
	v_cndmask_b32_e64 v91, v91, 0, s[72:73]
	v_exp_f32_e32 v64, v64
	v_exp_f32_e32 v65, v65
	s_waitcnt lgkmcnt(6)
	v_mfma_f32_32x32x16_bf16 v[48:63], v[148:151], v[88:91], v[48:63]
	ds_read_b128 v[148:151], v187 offset:13888
	v_exp_f32_e32 v66, v66
	v_exp_f32_e32 v67, v67
	s_waitcnt lgkmcnt(4)
	v_mfma_f32_32x32x16_bf16 v[32:47], v[124:127], v[88:91], v[32:47]
	ds_read_b128 v[124:127], v187 offset:9312
	v_exp_f32_e32 v68, v68
	v_exp_f32_e32 v69, v69
	v_mfma_f32_32x32x16_bf16 v[238:253], v[108:111], v[136:139], v[238:253]
	v_exp_f32_e32 v70, v70
	v_exp_f32_e32 v71, v71
	v_mfma_f32_32x32x16_bf16 v[222:237], v[112:115], v[136:139], v[222:237]
	v_add_f32_e32 v164, v64, v164
	v_add_f32_e32 v165, v65, v165
	v_add_f32_e32 v164, v66, v164
	v_add_f32_e32 v165, v67, v165
	v_cvt_pk_bf16_f32 v64, v64, v65
	v_cvt_pk_bf16_f32 v65, v66, v67
	v_add_f32_e32 v164, v68, v164
	v_add_f32_e32 v165, v69, v165
	v_add_f32_e32 v164, v70, v164
	v_add_f32_e32 v165, v71, v165
	v_cvt_pk_bf16_f32 v66, v68, v69
	v_cvt_pk_bf16_f32 v67, v70, v71
	v_cndmask_b32_e64 v64, v64, 0, s[72:73]
	v_cndmask_b32_e64 v65, v65, 0, s[72:73]
	v_cndmask_b32_e64 v66, v66, 0, s[72:73]
	v_cndmask_b32_e64 v67, v67, 0, s[72:73]
	v_exp_f32_e32 v72, v72
	v_exp_f32_e32 v73, v73
	s_waitcnt lgkmcnt(4)
	v_mfma_f32_32x32x16_bf16 v[48:63], v[144:147], v[64:67], v[48:63]
	ds_read_b128 v[144:147], v187 offset:13920
	v_exp_f32_e32 v74, v74
	v_exp_f32_e32 v75, v75
	s_waitcnt lgkmcnt(2)
	v_mfma_f32_32x32x16_bf16 v[32:47], v[148:151], v[64:67], v[32:47]
	v_exp_f32_e32 v76, v76
	v_exp_f32_e32 v77, v77
	v_mfma_f32_32x32x16_bf16 v[238:253], v[116:119], v[140:143], v[238:253]
	v_exp_f32_e32 v78, v78
	v_exp_f32_e32 v79, v79
	v_mfma_f32_32x32x16_bf16 v[222:237], v[120:123], v[140:143], v[222:237]
	v_add_f32_e32 v164, v72, v164
	v_add_f32_e32 v165, v73, v165
	v_add_f32_e32 v164, v74, v164
	v_add_f32_e32 v165, v75, v165
	v_cvt_pk_bf16_f32 v72, v72, v73
	v_cvt_pk_bf16_f32 v73, v74, v75
	v_add_f32_e32 v164, v76, v164
	v_add_f32_e32 v165, v77, v165
	v_add_f32_e32 v164, v78, v164
	v_add_f32_e32 v165, v79, v165
	v_cvt_pk_bf16_f32 v74, v76, v77
	v_cvt_pk_bf16_f32 v75, v78, v79
	v_cndmask_b32_e64 v72, v72, 0, s[72:73]
	v_cndmask_b32_e64 v73, v73, 0, s[72:73]
	v_cndmask_b32_e64 v74, v74, 0, s[72:73]
	v_cndmask_b32_e64 v75, v75, 0, s[72:73]
	s_nop 1
	s_waitcnt lgkmcnt(1)
	v_mfma_f32_32x32x16_bf16 v[48:63], v[124:127], v[72:75], v[48:63]
	s_waitcnt lgkmcnt(0)
	v_mfma_f32_32x32x16_bf16 v[32:47], v[144:147], v[72:75], v[32:47]
	v_add_f32_e32 v164, v164, v165
	v_cndmask_b32_e64 v164, v164, 0, s[72:73]
	v_add_f32_e32 v106, v106, v164
	v_cmp_lt_f32_e32 vcc, 0x43800000, v164
	s_cbranch_vccz .Lsel_noresc_0b
	s_nop 15
	s_nop 15
	v_mov_b32_e32 v107, v164
	s_nop 1
	v_permlane32_swap_b32_e32 v164, v107
	v_add_f32_e32 v164, v164, v107
	v_log_f32_e32 v160, v164
	s_nop 0
	v_max_f32_e32 v160, 0, v160
	v_exp_f32_e64 v162, -v160
	v_sub_f32_e32 v2, v2, v160
	v_sub_f32_e32 v3, v3, v160
	v_sub_f32_e32 v4, v4, v160
	v_sub_f32_e32 v5, v5, v160
	v_sub_f32_e32 v6, v6, v160
	v_sub_f32_e32 v7, v7, v160
	v_sub_f32_e32 v8, v8, v160
	v_sub_f32_e32 v9, v9, v160
	v_sub_f32_e32 v10, v10, v160
	v_sub_f32_e32 v11, v11, v160
	v_sub_f32_e32 v12, v12, v160
	v_sub_f32_e32 v13, v13, v160
	v_sub_f32_e32 v14, v14, v160
	v_sub_f32_e32 v15, v15, v160
	v_sub_f32_e32 v16, v16, v160
	v_sub_f32_e32 v17, v17, v160
	v_mul_f32_e32 v106, v106, v162
	v_pk_mul_f32 v[48:49], v[48:49], v[162:163] op_sel_hi:[1,0]
	v_pk_mul_f32 v[32:33], v[32:33], v[162:163] op_sel_hi:[1,0]
	v_pk_mul_f32 v[50:51], v[50:51], v[162:163] op_sel_hi:[1,0]
	v_pk_mul_f32 v[34:35], v[34:35], v[162:163] op_sel_hi:[1,0]
	v_pk_mul_f32 v[52:53], v[52:53], v[162:163] op_sel_hi:[1,0]
	v_pk_mul_f32 v[36:37], v[36:37], v[162:163] op_sel_hi:[1,0]
	v_pk_mul_f32 v[54:55], v[54:55], v[162:163] op_sel_hi:[1,0]
	v_pk_mul_f32 v[38:39], v[38:39], v[162:163] op_sel_hi:[1,0]
	v_pk_mul_f32 v[56:57], v[56:57], v[162:163] op_sel_hi:[1,0]
	v_pk_mul_f32 v[40:41], v[40:41], v[162:163] op_sel_hi:[1,0]
	v_pk_mul_f32 v[58:59], v[58:59], v[162:163] op_sel_hi:[1,0]
	v_pk_mul_f32 v[42:43], v[42:43], v[162:163] op_sel_hi:[1,0]
	v_pk_mul_f32 v[60:61], v[60:61], v[162:163] op_sel_hi:[1,0]
	v_pk_mul_f32 v[44:45], v[44:45], v[162:163] op_sel_hi:[1,0]
	v_pk_mul_f32 v[62:63], v[62:63], v[162:163] op_sel_hi:[1,0]
	v_pk_mul_f32 v[46:47], v[46:47], v[162:163] op_sel_hi:[1,0]
	v_pk_add_f32 v[238:239], v[238:239], v[160:161] op_sel_hi:[1,0] neg_lo:[0,1] neg_hi:[0,1]
	v_pk_add_f32 v[222:223], v[222:223], v[160:161] op_sel_hi:[1,0] neg_lo:[0,1] neg_hi:[0,1]
	v_pk_add_f32 v[240:241], v[240:241], v[160:161] op_sel_hi:[1,0] neg_lo:[0,1] neg_hi:[0,1]
	v_pk_add_f32 v[224:225], v[224:225], v[160:161] op_sel_hi:[1,0] neg_lo:[0,1] neg_hi:[0,1]
	v_pk_add_f32 v[242:243], v[242:243], v[160:161] op_sel_hi:[1,0] neg_lo:[0,1] neg_hi:[0,1]
	v_pk_add_f32 v[226:227], v[226:227], v[160:161] op_sel_hi:[1,0] neg_lo:[0,1] neg_hi:[0,1]
	v_pk_add_f32 v[244:245], v[244:245], v[160:161] op_sel_hi:[1,0] neg_lo:[0,1] neg_hi:[0,1]
	v_pk_add_f32 v[228:229], v[228:229], v[160:161] op_sel_hi:[1,0] neg_lo:[0,1] neg_hi:[0,1]
	v_pk_add_f32 v[246:247], v[246:247], v[160:161] op_sel_hi:[1,0] neg_lo:[0,1] neg_hi:[0,1]
	v_pk_add_f32 v[230:231], v[230:231], v[160:161] op_sel_hi:[1,0] neg_lo:[0,1] neg_hi:[0,1]
	v_pk_add_f32 v[248:249], v[248:249], v[160:161] op_sel_hi:[1,0] neg_lo:[0,1] neg_hi:[0,1]
	v_pk_add_f32 v[232:233], v[232:233], v[160:161] op_sel_hi:[1,0] neg_lo:[0,1] neg_hi:[0,1]
	v_pk_add_f32 v[250:251], v[250:251], v[160:161] op_sel_hi:[1,0] neg_lo:[0,1] neg_hi:[0,1]
	v_pk_add_f32 v[234:235], v[234:235], v[160:161] op_sel_hi:[1,0] neg_lo:[0,1] neg_hi:[0,1]
	v_pk_add_f32 v[252:253], v[252:253], v[160:161] op_sel_hi:[1,0] neg_lo:[0,1] neg_hi:[0,1]
	v_pk_add_f32 v[236:237], v[236:237], v[160:161] op_sel_hi:[1,0] neg_lo:[0,1] neg_hi:[0,1]
	s_nop 1

.Lsel_nodiag_1b:
	v_add_u32_e32 v187, s81, v208
	ds_read_b128 v[124:127], v187 offset:9216
	ds_read_b128 v[144:147], v187 offset:13824
	ds_read_b128 v[148:151], v187 offset:9248
	v_exp_f32_e32 v238, v238
	v_exp_f32_e32 v239, v239
	v_exp_f32_e32 v240, v240
	v_exp_f32_e32 v241, v241
	v_exp_f32_e32 v242, v242
	v_exp_f32_e32 v243, v243
	v_exp_f32_e32 v244, v244
	v_exp_f32_e32 v245, v245
	s_waitcnt lgkmcnt(6)
	v_mfma_f32_32x32x16_bf16 v[80:95], v[108:111], v[128:131], v[2:17]
	ds_read_b128 v[108:111], v0 offset:64
	s_waitcnt lgkmcnt(6)
	v_mfma_f32_32x32x16_bf16 v[64:79], v[112:115], v[128:131], v[2:17]
	ds_read_b128 v[112:115], v0 offset:4672
	v_add_f32_e32 v164, 0, v238
	v_add_f32_e32 v165, 0, v239
	v_add_f32_e32 v164, v240, v164
	v_add_f32_e32 v165, v241, v165
	v_cvt_pk_bf16_f32 v238, v238, v239
	v_cvt_pk_bf16_f32 v239, v240, v241
	v_add_f32_e32 v164, v242, v164
	v_add_f32_e32 v165, v243, v165
	v_add_f32_e32 v164, v244, v164
	v_add_f32_e32 v165, v245, v165
	v_cvt_pk_bf16_f32 v240, v242, v243
	v_cvt_pk_bf16_f32 v241, v244, v245
	v_cndmask_b32_e64 v238, v238, 0, s[72:73]
	v_cndmask_b32_e64 v239, v239, 0, s[72:73]
	v_cndmask_b32_e64 v240, v240, 0, s[72:73]
	v_cndmask_b32_e64 v241, v241, 0, s[72:73]
	v_exp_f32_e32 v246, v246
	v_exp_f32_e32 v247, v247
	s_waitcnt lgkmcnt(4)
	v_mfma_f32_32x32x16_bf16 v[48:63], v[124:127], v[238:241], v[48:63]
	ds_read_b128 v[124:127], v187 offset:13856
	v_exp_f32_e32 v248, v248
	v_exp_f32_e32 v249, v249
	s_waitcnt lgkmcnt(4)
	v_mfma_f32_32x32x16_bf16 v[32:47], v[144:147], v[238:241], v[32:47]
	ds_read_b128 v[144:147], v187 offset:9280
	v_exp_f32_e32 v250, v250
	v_exp_f32_e32 v251, v251
	v_mfma_f32_32x32x16_bf16 v[80:95], v[116:119], v[132:135], v[80:95]
	ds_read_b128 v[116:119], v0 offset:96
	v_exp_f32_e32 v252, v252
	v_exp_f32_e32 v253, v253
	v_mfma_f32_32x32x16_bf16 v[64:79], v[120:123], v[132:135], v[64:79]
	ds_read_b128 v[120:123], v0 offset:4704
	v_add_f32_e32 v164, v246, v164
	v_add_f32_e32 v165, v247, v165
	v_add_f32_e32 v164, v248, v164
	v_add_f32_e32 v165, v249, v165
	v_cvt_pk_bf16_f32 v246, v246, v247
	v_cvt_pk_bf16_f32 v247, v248, v249
	v_add_f32_e32 v164, v250, v164
	v_add_f32_e32 v165, v251, v165
	v_add_f32_e32 v164, v252, v164
	v_add_f32_e32 v165, v253, v165
	v_cvt_pk_bf16_f32 v248, v250, v251
	v_cvt_pk_bf16_f32 v249, v252, v253
	v_cndmask_b32_e64 v246, v246, 0, s[72:73]
	v_cndmask_b32_e64 v247, v247, 0, s[72:73]
	v_cndmask_b32_e64 v248, v248, 0, s[72:73]
	v_cndmask_b32_e64 v249, v249, 0, s[72:73]
	v_exp_f32_e32 v222, v222
	v_exp_f32_e32 v223, v223
	s_waitcnt lgkmcnt(6)
	v_mfma_f32_32x32x16_bf16 v[48:63], v[148:151], v[246:249], v[48:63]
	ds_read_b128 v[148:151], v187 offset:13888
	v_exp_f32_e32 v224, v224
	v_exp_f32_e32 v225, v225
	s_waitcnt lgkmcnt(4)
	v_mfma_f32_32x32x16_bf16 v[32:47], v[124:127], v[246:249], v[32:47]
	ds_read_b128 v[124:127], v187 offset:9312
	v_exp_f32_e32 v226, v226
	v_exp_f32_e32 v227, v227
	v_mfma_f32_32x32x16_bf16 v[80:95], v[108:111], v[136:139], v[80:95]
	v_exp_f32_e32 v228, v228
	v_exp_f32_e32 v229, v229
	v_mfma_f32_32x32x16_bf16 v[64:79], v[112:115], v[136:139], v[64:79]
	v_add_f32_e32 v164, v222, v164
	v_add_f32_e32 v165, v223, v165
	v_add_f32_e32 v164, v224, v164
	v_add_f32_e32 v165, v225, v165
	v_cvt_pk_bf16_f32 v222, v222, v223
	v_cvt_pk_bf16_f32 v223, v224, v225
	v_add_f32_e32 v164, v226, v164
	v_add_f32_e32 v165, v227, v165
	v_add_f32_e32 v164, v228, v164
	v_add_f32_e32 v165, v229, v165
	v_cvt_pk_bf16_f32 v224, v226, v227
	v_cvt_pk_bf16_f32 v225, v228, v229
	v_cndmask_b32_e64 v222, v222, 0, s[72:73]
	v_cndmask_b32_e64 v223, v223, 0, s[72:73]
	v_cndmask_b32_e64 v224, v224, 0, s[72:73]
	v_cndmask_b32_e64 v225, v225, 0, s[72:73]
	v_exp_f32_e32 v230, v230
	v_exp_f32_e32 v231, v231
	s_waitcnt lgkmcnt(4)
	v_mfma_f32_32x32x16_bf16 v[48:63], v[144:147], v[222:225], v[48:63]
	ds_read_b128 v[144:147], v187 offset:13920
	v_exp_f32_e32 v232, v232
	v_exp_f32_e32 v233, v233
	s_waitcnt lgkmcnt(2)
	v_mfma_f32_32x32x16_bf16 v[32:47], v[148:151], v[222:225], v[32:47]
	v_exp_f32_e32 v234, v234
	v_exp_f32_e32 v235, v235
	v_mfma_f32_32x32x16_bf16 v[80:95], v[116:119], v[140:143], v[80:95]
	v_exp_f32_e32 v236, v236
	v_exp_f32_e32 v237, v237
	v_mfma_f32_32x32x16_bf16 v[64:79], v[120:123], v[140:143], v[64:79]
	v_add_f32_e32 v164, v230, v164
	v_add_f32_e32 v165, v231, v165
	v_add_f32_e32 v164, v232, v164
	v_add_f32_e32 v165, v233, v165
	v_cvt_pk_bf16_f32 v230, v230, v231
	v_cvt_pk_bf16_f32 v231, v232, v233
	v_add_f32_e32 v164, v234, v164
	v_add_f32_e32 v165, v235, v165
	v_add_f32_e32 v164, v236, v164
	v_add_f32_e32 v165, v237, v165
	v_cvt_pk_bf16_f32 v232, v234, v235
	v_cvt_pk_bf16_f32 v233, v236, v237
	v_cndmask_b32_e64 v230, v230, 0, s[72:73]
	v_cndmask_b32_e64 v231, v231, 0, s[72:73]
	v_cndmask_b32_e64 v232, v232, 0, s[72:73]
	v_cndmask_b32_e64 v233, v233, 0, s[72:73]
	s_nop 1
	s_waitcnt lgkmcnt(1)
	v_mfma_f32_32x32x16_bf16 v[48:63], v[124:127], v[230:233], v[48:63]
	s_waitcnt lgkmcnt(0)
	v_mfma_f32_32x32x16_bf16 v[32:47], v[144:147], v[230:233], v[32:47]
	v_add_f32_e32 v164, v164, v165
	v_cndmask_b32_e64 v164, v164, 0, s[72:73]
	v_add_f32_e32 v106, v106, v164
	v_cmp_lt_f32_e32 vcc, 0x43800000, v164
	s_cbranch_vccz .Lsel_noresc_1b
	s_nop 15
	s_nop 15
	v_mov_b32_e32 v107, v164
	s_nop 1
	v_permlane32_swap_b32_e32 v164, v107
	v_add_f32_e32 v164, v164, v107
	v_log_f32_e32 v160, v164
	s_nop 0
	v_max_f32_e32 v160, 0, v160
	v_exp_f32_e64 v162, -v160
	v_sub_f32_e32 v2, v2, v160
	v_sub_f32_e32 v3, v3, v160
	v_sub_f32_e32 v4, v4, v160
	v_sub_f32_e32 v5, v5, v160
	v_sub_f32_e32 v6, v6, v160
	v_sub_f32_e32 v7, v7, v160
	v_sub_f32_e32 v8, v8, v160
	v_sub_f32_e32 v9, v9, v160
	v_sub_f32_e32 v10, v10, v160
	v_sub_f32_e32 v11, v11, v160
	v_sub_f32_e32 v12, v12, v160
	v_sub_f32_e32 v13, v13, v160
	v_sub_f32_e32 v14, v14, v160
	v_sub_f32_e32 v15, v15, v160
	v_sub_f32_e32 v16, v16, v160
	v_sub_f32_e32 v17, v17, v160
	v_mul_f32_e32 v106, v106, v162
	v_pk_mul_f32 v[48:49], v[48:49], v[162:163] op_sel_hi:[1,0]
	v_pk_mul_f32 v[32:33], v[32:33], v[162:163] op_sel_hi:[1,0]
	v_pk_mul_f32 v[50:51], v[50:51], v[162:163] op_sel_hi:[1,0]
	v_pk_mul_f32 v[34:35], v[34:35], v[162:163] op_sel_hi:[1,0]
	v_pk_mul_f32 v[52:53], v[52:53], v[162:163] op_sel_hi:[1,0]
	v_pk_mul_f32 v[36:37], v[36:37], v[162:163] op_sel_hi:[1,0]
	v_pk_mul_f32 v[54:55], v[54:55], v[162:163] op_sel_hi:[1,0]
	v_pk_mul_f32 v[38:39], v[38:39], v[162:163] op_sel_hi:[1,0]
	v_pk_mul_f32 v[56:57], v[56:57], v[162:163] op_sel_hi:[1,0]
	v_pk_mul_f32 v[40:41], v[40:41], v[162:163] op_sel_hi:[1,0]
	v_pk_mul_f32 v[58:59], v[58:59], v[162:163] op_sel_hi:[1,0]
	v_pk_mul_f32 v[42:43], v[42:43], v[162:163] op_sel_hi:[1,0]
	v_pk_mul_f32 v[60:61], v[60:61], v[162:163] op_sel_hi:[1,0]
	v_pk_mul_f32 v[44:45], v[44:45], v[162:163] op_sel_hi:[1,0]
	v_pk_mul_f32 v[62:63], v[62:63], v[162:163] op_sel_hi:[1,0]
	v_pk_mul_f32 v[46:47], v[46:47], v[162:163] op_sel_hi:[1,0]
	v_pk_add_f32 v[80:81], v[80:81], v[160:161] op_sel_hi:[1,0] neg_lo:[0,1] neg_hi:[0,1]
	v_pk_add_f32 v[64:65], v[64:65], v[160:161] op_sel_hi:[1,0] neg_lo:[0,1] neg_hi:[0,1]
	v_pk_add_f32 v[82:83], v[82:83], v[160:161] op_sel_hi:[1,0] neg_lo:[0,1] neg_hi:[0,1]
	v_pk_add_f32 v[66:67], v[66:67], v[160:161] op_sel_hi:[1,0] neg_lo:[0,1] neg_hi:[0,1]
	v_pk_add_f32 v[84:85], v[84:85], v[160:161] op_sel_hi:[1,0] neg_lo:[0,1] neg_hi:[0,1]
	v_pk_add_f32 v[68:69], v[68:69], v[160:161] op_sel_hi:[1,0] neg_lo:[0,1] neg_hi:[0,1]
	v_pk_add_f32 v[86:87], v[86:87], v[160:161] op_sel_hi:[1,0] neg_lo:[0,1] neg_hi:[0,1]
	v_pk_add_f32 v[70:71], v[70:71], v[160:161] op_sel_hi:[1,0] neg_lo:[0,1] neg_hi:[0,1]
	v_pk_add_f32 v[88:89], v[88:89], v[160:161] op_sel_hi:[1,0] neg_lo:[0,1] neg_hi:[0,1]
	v_pk_add_f32 v[72:73], v[72:73], v[160:161] op_sel_hi:[1,0] neg_lo:[0,1] neg_hi:[0,1]
	v_pk_add_f32 v[90:91], v[90:91], v[160:161] op_sel_hi:[1,0] neg_lo:[0,1] neg_hi:[0,1]
	v_pk_add_f32 v[74:75], v[74:75], v[160:161] op_sel_hi:[1,0] neg_lo:[0,1] neg_hi:[0,1]
	v_pk_add_f32 v[92:93], v[92:93], v[160:161] op_sel_hi:[1,0] neg_lo:[0,1] neg_hi:[0,1]
	v_pk_add_f32 v[76:77], v[76:77], v[160:161] op_sel_hi:[1,0] neg_lo:[0,1] neg_hi:[0,1]
	v_pk_add_f32 v[94:95], v[94:95], v[160:161] op_sel_hi:[1,0] neg_lo:[0,1] neg_hi:[0,1]
	v_pk_add_f32 v[78:79], v[78:79], v[160:161] op_sel_hi:[1,0] neg_lo:[0,1] neg_hi:[0,1]
	s_nop 1
